# v026: v024 + hazard-slot filling in GEMM loops (m0 write moved ahead of the DMA address add, s_nop dropped, 7 sites)
# baseline (speedup 1.0000x reference)
; #define PG8_STAGE(bufoff, gbase, voff) do { _Pragma("unroll") for (int _i = 0; _i < 2; ++_i) \
;         __builtin_amdgcn_global_load_lds((const unsigned*)((const char*)(gbase) + (voff)[_i]), (PG8_LAS unsigned*)(lds + (bufoff) + ldsw + _i * 8192), 16, 0, 0); } while (0)
; #define PG8_LDA(dst, b, h) do { _Pragma("unroll") for (int m = 0; m < 4; ++m) _Pragma("unroll") for (int k = 0; k < 2; ++k) dst[m][k] = *(const PG8_LAS bf16x8*)(lds + PG8_SA(b, h) + aoff + m * 2048 + k * 1024); } while (0)
; #define PG8_LDB(dst, b, h) do { _Pragma("unroll") for (int n = 0; n < 2; ++n) _Pragma("unroll") for (int k = 0; k < 2; ++k) dst[n][k] = *(const PG8_LAS bf16x8*)(lds + PG8_SB(b, h) + boff + n * 2048 + k * 1024); } while (0)
; #define PG8_MMA(ai, bj, At, Bt) do { __builtin_amdgcn_s_setprio(1); _Pragma("unroll") for (int m = 0; m < 4; ++m) _Pragma("unroll") for (int n = 0; n < 2; ++n) _Pragma("unroll") for (int k = 0; k < 2; ++k) \
;         acc[ai][bj][m][n] = __builtin_amdgcn_mfma_f32_16x16x32_bf16(Bt[n][k], At[m][k], acc[ai][bj][m][n], 0, 0, 0); __builtin_amdgcn_s_setprio(0); } while (0)
; #define PG8_WAIT_V(n) asm volatile("s_waitcnt vmcnt(" #n ")" ::: "memory")
; #define PG8_WAIT_L(n) asm volatile("s_waitcnt lgkmcnt(" #n ")" ::: "memory")
; template <class Epi, class Sched, bool ALIGN_EPI = false, bool SP2 = false>
; __device__ __forceinline__ void gemm_phase(PG8_LAS unsigned char* lds, const Gemm g, const Sched& S, const Epi& E, int tid_) {
;     ...
;             const bool last = (t == nt - 2);
;             const char* a1 = cA + (size_t)(t + 1) * kstep;
;             const char* a2 = last ? nA : cA + (size_t)(t + 2) * kstep; const char* b2 = last ? nB : cB + (size_t)(t + 2) * kstep;
;             const char* a3 = a2 + kstep; const char* b3 = b2 + kstep;
;             if (last && has_next) S.a_ready(nxt);
;             if constexpr (SP2) {
;             PG8_LDB(B0, 0, 0); PG8_LDB(B1, 0, 1); PG8_SCHED; PG8_LDA(At, 0, 0); PG8_STAGE(PG8_SA(1, 1), a1 + hstep, voffA);
;             PG8_WAIT_V(8); PG8_WAIT_L(0); PG8_BAR; PG8_MMA(0, 0, At, B0); PG8_MMA(0, 1, At, B1); PG8_BAR; PG8_SCHED;
;             PG8_LDA(At, 0, 1); PG8_STAGE(PG8_SB(0, 0), b2, voffB); PG8_STAGE(PG8_SB(0, 1), b2 + hstep, voffB); PG8_STAGE(PG8_SA(0, 0), a2, voffA);
;             PG8_WAIT_V(8); PG8_WAIT_L(0); PG8_BAR; PG8_MMA(1, 0, At, B0); PG8_MMA(1, 1, At, B1); PG8_BAR; PG8_SCHED;
.LBB0_226:
	v_add_u32_e32 v140, 0x10000, v143
	ds_read_b128 v[146:149], v140
	ds_read_b128 v[150:153], v140 offset:1024
	ds_read_b128 v[154:157], v140 offset:2048
	ds_read_b128 v[158:161], v140 offset:3072
	v_add_u32_e32 v140, 0x14000, v143
	ds_read_b128 v[162:165], v140
	ds_read_b128 v[166:169], v140 offset:1024
	ds_read_b128 v[170:173], v140 offset:2048
	ds_read_b128 v[174:177], v140 offset:3072
	s_add_i32 s91, s64, 2
	s_add_u32 s21, s70, 0x80
	s_addc_u32 s65, s71, 0
	s_add_i32 s94, 0, 0x10000
	s_cmp_eq_u32 s55, s64
	s_cselect_b32 s65, s43, s65
	s_cselect_b32 s64, s42, s21
	s_cselect_b32 s93, s61, s81
	s_cselect_b32 s92, s60, s80
	s_add_i32 s21, 0, 0x14000
	v_lshl_add_u64 v[140:141], s[70:71], 0, v[138:139]
	s_add_i32 m0, s11, 0xc000
	ds_read_b128 v[178:181], v145
	ds_read_b128 v[182:185], v145 offset:1024
	ds_read_b128 v[186:189], v145 offset:2048
	ds_read_b128 v[200:203], v145 offset:3072
	ds_read_b128 v[204:207], v145 offset:4096
	ds_read_b128 v[208:211], v145 offset:5120
	ds_read_b128 v[214:217], v145 offset:6144
	ds_read_b128 v[232:235], v145 offset:7168
	global_load_lds_dwordx4 v[140:141], off
	s_add_i32 m0, s11, 0xe000
	v_lshl_add_u64 v[140:141], s[70:71], 0, v[136:137]
	global_load_lds_dwordx4 v[140:141], off
	s_waitcnt vmcnt(8)
	s_waitcnt lgkmcnt(0)
	s_barrier
	s_setprio 1
	s_waitcnt lgkmcnt(0)
	v_mfma_f32_16x16x32_bf16 v[126:129], v[146:149], v[178:181], v[126:129]
	v_mfma_f32_16x16x32_bf16 v[122:125], v[154:157], v[178:181], v[122:125]
	v_mfma_f32_16x16x32_bf16 v[110:113], v[146:149], v[186:189], v[110:113]
	v_mfma_f32_16x16x32_bf16 v[106:109], v[154:157], v[186:189], v[106:109]
	v_mfma_f32_16x16x32_bf16 v[94:97], v[146:149], v[204:207], v[94:97]
	v_mfma_f32_16x16x32_bf16 v[90:93], v[154:157], v[204:207], v[90:93]
	v_mfma_f32_16x16x32_bf16 v[78:81], v[146:149], v[214:217], v[78:81]
	v_mfma_f32_16x16x32_bf16 v[74:77], v[154:157], v[214:217], v[74:77]
	v_mfma_f32_16x16x32_bf16 v[126:129], v[150:153], v[182:185], v[126:129]
	v_mfma_f32_16x16x32_bf16 v[122:125], v[158:161], v[182:185], v[122:125]
	v_mfma_f32_16x16x32_bf16 v[110:113], v[150:153], v[200:203], v[110:113]
	v_mfma_f32_16x16x32_bf16 v[106:109], v[158:161], v[200:203], v[106:109]
	v_mfma_f32_16x16x32_bf16 v[94:97], v[150:153], v[208:211], v[94:97]
	v_mfma_f32_16x16x32_bf16 v[90:93], v[158:161], v[208:211], v[90:93]
	v_mfma_f32_16x16x32_bf16 v[78:81], v[150:153], v[232:235], v[78:81]
	v_mfma_f32_16x16x32_bf16 v[74:77], v[158:161], v[232:235], v[74:77]
	s_setprio 0
	s_setprio 1
	v_mfma_f32_16x16x32_bf16 v[118:121], v[162:165], v[178:181], v[118:121]
	v_mfma_f32_16x16x32_bf16 v[114:117], v[170:173], v[178:181], v[114:117]
	v_mfma_f32_16x16x32_bf16 v[102:105], v[162:165], v[186:189], v[102:105]
	v_mfma_f32_16x16x32_bf16 v[98:101], v[170:173], v[186:189], v[98:101]
	v_mfma_f32_16x16x32_bf16 v[86:89], v[162:165], v[204:207], v[86:89]
	v_mfma_f32_16x16x32_bf16 v[82:85], v[170:173], v[204:207], v[82:85]
	v_mfma_f32_16x16x32_bf16 v[70:73], v[162:165], v[214:217], v[70:73]
	v_mfma_f32_16x16x32_bf16 v[66:69], v[170:173], v[214:217], v[66:69]
	v_mfma_f32_16x16x32_bf16 v[118:121], v[166:169], v[182:185], v[118:121]
	v_mfma_f32_16x16x32_bf16 v[114:117], v[174:177], v[182:185], v[114:117]
	v_mfma_f32_16x16x32_bf16 v[102:105], v[166:169], v[200:203], v[102:105]
	v_mfma_f32_16x16x32_bf16 v[98:101], v[174:177], v[200:203], v[98:101]
	v_mfma_f32_16x16x32_bf16 v[86:89], v[166:169], v[208:211], v[86:89]
	v_mfma_f32_16x16x32_bf16 v[82:85], v[174:177], v[208:211], v[82:85]
	v_mfma_f32_16x16x32_bf16 v[70:73], v[166:169], v[232:235], v[70:73]
	v_mfma_f32_16x16x32_bf16 v[66:69], v[174:177], v[232:235], v[66:69]
	s_setprio 0
	s_barrier
	s_add_i32 s94, s94, s9
	v_lshl_add_u64 v[140:141], s[92:93], 0, v[0:1]
	s_mov_b32 m0, s94
	ds_read_b128 v[178:181], v145 offset:16384
	ds_read_b128 v[182:185], v145 offset:17408
	ds_read_b128 v[186:189], v145 offset:18432
	ds_read_b128 v[200:203], v145 offset:19456
	ds_read_b128 v[204:207], v145 offset:20480
	ds_read_b128 v[208:211], v145 offset:21504
	ds_read_b128 v[214:217], v145 offset:22528
	ds_read_b128 v[232:235], v145 offset:23552
	global_load_lds_dwordx4 v[140:141], off
	s_add_i32 m0, s94, 0x2000
	v_lshl_add_u64 v[190:191], s[92:93], 0, v[134:135]
	s_add_u32 s92, s92, s38
	s_addc_u32 s93, s93, s39
	s_add_i32 s21, s21, s9
	global_load_lds_dwordx4 v[190:191], off
	v_lshl_add_u64 v[236:237], s[92:93], 0, v[0:1]
	s_mov_b32 m0, s21
	v_lshl_add_u64 v[238:239], s[92:93], 0, v[134:135]
	global_load_lds_dwordx4 v[236:237], off
	s_add_i32 m0, s21, 0x2000
	v_lshl_add_u64 v[240:241], s[64:65], 0, v[130:131]
	global_load_lds_dwordx4 v[238:239], off
	s_mov_b32 m0, s11
	v_lshl_add_u64 v[242:243], s[64:65], 0, v[132:133]
	global_load_lds_dwordx4 v[240:241], off
	s_mov_b32 m0, s12
	s_nop 0
	global_load_lds_dwordx4 v[242:243], off
	s_waitcnt vmcnt(8)
	s_waitcnt lgkmcnt(0)
	s_barrier
; #define PG8_STAGE(bufoff, gbase, voff) do { _Pragma("unroll") for (int _i = 0; _i < 2; ++_i) \
;         __builtin_amdgcn_global_load_lds((const unsigned*)((const char*)(gbase) + (voff)[_i]), (PG8_LAS unsigned*)(lds + (bufoff) + ldsw + _i * 8192), 16, 0, 0); } while (0)
; #define PG8_LDA(dst, b, h) do { _Pragma("unroll") for (int m = 0; m < 4; ++m) _Pragma("unroll") for (int k = 0; k < 2; ++k) dst[m][k] = *(const PG8_LAS bf16x8*)(lds + PG8_SA(b, h) + aoff + m * 2048 + k * 1024); } while (0)
; #define PG8_LDB(dst, b, h) do { _Pragma("unroll") for (int n = 0; n < 2; ++n) _Pragma("unroll") for (int k = 0; k < 2; ++k) dst[n][k] = *(const PG8_LAS bf16x8*)(lds + PG8_SB(b, h) + boff + n * 2048 + k * 1024); } while (0)
; #define PG8_MMA(ai, bj, At, Bt) do { __builtin_amdgcn_s_setprio(1); _Pragma("unroll") for (int m = 0; m < 4; ++m) _Pragma("unroll") for (int n = 0; n < 2; ++n) _Pragma("unroll") for (int k = 0; k < 2; ++k) \
;         acc[ai][bj][m][n] = __builtin_amdgcn_mfma_f32_16x16x32_bf16(Bt[n][k], At[m][k], acc[ai][bj][m][n], 0, 0, 0); __builtin_amdgcn_s_setprio(0); } while (0)
; #define PG8_WAIT_V(n) asm volatile("s_waitcnt vmcnt(" #n ")" ::: "memory")
; #define PG8_WAIT_L(n) asm volatile("s_waitcnt lgkmcnt(" #n ")" ::: "memory")
; #define PG8_BAR __builtin_amdgcn_s_barrier()
; #define PG8_SCHED __builtin_amdgcn_sched_barrier(0)
; template <class Epi, class Sched, bool ALIGN_EPI = false, bool SP2 = false>
; __device__ __forceinline__ void gemm_phase(PG8_LAS unsigned char* lds, const Gemm g, const Sched& S, const Epi& E, int tid_) {
;     ...
;             PG8_WAIT_V(8); PG8_WAIT_L(0); PG8_BAR; PG8_MMA(1, 0, At, B0); PG8_MMA(1, 1, At, B1); PG8_BAR; PG8_SCHED;
;             PG8_LDB(B0, 1, 0); PG8_LDB(B1, 1, 1); PG8_SCHED; PG8_LDA(At, 1, 0); PG8_STAGE(PG8_SA(0, 1), a2 + hstep, voffA);
;             PG8_WAIT_V(8); PG8_WAIT_L(0); PG8_BAR; PG8_MMA(0, 0, At, B0); PG8_MMA(0, 1, At, B1); PG8_BAR; PG8_SCHED;
	s_setprio 1
	s_waitcnt lgkmcnt(0)
	v_mfma_f32_16x16x32_bf16 v[62:65], v[146:149], v[178:181], v[62:65]
	v_mfma_f32_16x16x32_bf16 v[58:61], v[154:157], v[178:181], v[58:61]
	v_mfma_f32_16x16x32_bf16 v[46:49], v[146:149], v[186:189], v[46:49]
	v_mfma_f32_16x16x32_bf16 v[42:45], v[154:157], v[186:189], v[42:45]
	v_mfma_f32_16x16x32_bf16 v[30:33], v[146:149], v[204:207], v[30:33]
	v_mfma_f32_16x16x32_bf16 v[26:29], v[154:157], v[204:207], v[26:29]
	v_mfma_f32_16x16x32_bf16 v[14:17], v[146:149], v[214:217], v[14:17]
	v_mfma_f32_16x16x32_bf16 v[10:13], v[154:157], v[214:217], v[10:13]
	v_mfma_f32_16x16x32_bf16 v[62:65], v[150:153], v[182:185], v[62:65]
	v_mfma_f32_16x16x32_bf16 v[58:61], v[158:161], v[182:185], v[58:61]
	v_mfma_f32_16x16x32_bf16 v[46:49], v[150:153], v[200:203], v[46:49]
	v_mfma_f32_16x16x32_bf16 v[42:45], v[158:161], v[200:203], v[42:45]
	v_mfma_f32_16x16x32_bf16 v[30:33], v[150:153], v[208:211], v[30:33]
	v_mfma_f32_16x16x32_bf16 v[26:29], v[158:161], v[208:211], v[26:29]
	v_mfma_f32_16x16x32_bf16 v[14:17], v[150:153], v[232:235], v[14:17]
	v_mfma_f32_16x16x32_bf16 v[10:13], v[158:161], v[232:235], v[10:13]
	s_setprio 0
	s_setprio 1
	v_mfma_f32_16x16x32_bf16 v[54:57], v[162:165], v[178:181], v[54:57]
	v_mfma_f32_16x16x32_bf16 v[50:53], v[170:173], v[178:181], v[50:53]
	v_mfma_f32_16x16x32_bf16 v[38:41], v[162:165], v[186:189], v[38:41]
	v_mfma_f32_16x16x32_bf16 v[34:37], v[170:173], v[186:189], v[34:37]
	v_mfma_f32_16x16x32_bf16 v[22:25], v[162:165], v[204:207], v[22:25]
	v_mfma_f32_16x16x32_bf16 v[18:21], v[170:173], v[204:207], v[18:21]
	v_mfma_f32_16x16x32_bf16 v[6:9], v[162:165], v[214:217], v[6:9]
	v_mfma_f32_16x16x32_bf16 v[2:5], v[170:173], v[214:217], v[2:5]
	v_mfma_f32_16x16x32_bf16 v[54:57], v[166:169], v[182:185], v[54:57]
	v_mfma_f32_16x16x32_bf16 v[50:53], v[174:177], v[182:185], v[50:53]
	v_mfma_f32_16x16x32_bf16 v[38:41], v[166:169], v[200:203], v[38:41]
	v_mfma_f32_16x16x32_bf16 v[34:37], v[174:177], v[200:203], v[34:37]
	v_mfma_f32_16x16x32_bf16 v[22:25], v[166:169], v[208:211], v[22:25]
	v_mfma_f32_16x16x32_bf16 v[18:21], v[174:177], v[208:211], v[18:21]
	v_mfma_f32_16x16x32_bf16 v[6:9], v[166:169], v[232:235], v[6:9]
	v_mfma_f32_16x16x32_bf16 v[2:5], v[174:177], v[232:235], v[2:5]
	s_setprio 0
	s_barrier
	s_add_i32 s21, 0, 0x18000
	s_add_i32 s92, 0, 0x1c000
	v_add_u32_e32 v158, s21, v143
	v_add_u32_e32 v174, s92, v143
	ds_read_b128 v[146:149], v158
	ds_read_b128 v[150:153], v158 offset:1024
	ds_read_b128 v[154:157], v158 offset:2048
	ds_read_b128 v[158:161], v158 offset:3072
	ds_read_b128 v[162:165], v174
	ds_read_b128 v[166:169], v174 offset:1024
	ds_read_b128 v[170:173], v174 offset:2048
	ds_read_b128 v[174:177], v174 offset:3072
	s_add_u32 s64, s64, s38
	s_addc_u32 s65, s65, s39
	s_mov_b32 m0, s13
	v_lshl_add_u64 v[244:245], s[64:65], 0, v[130:131]
	ds_read_b128 v[178:181], v145 offset:32768
	ds_read_b128 v[182:185], v145 offset:33792
	ds_read_b128 v[186:189], v145 offset:34816
	ds_read_b128 v[200:203], v145 offset:35840
	ds_read_b128 v[204:207], v145 offset:36864
	ds_read_b128 v[208:211], v145 offset:37888
	ds_read_b128 v[214:217], v145 offset:38912
	ds_read_b128 v[232:235], v145 offset:39936
	global_load_lds_dwordx4 v[244:245], off
	v_lshl_add_u64 v[244:245], s[64:65], 0, v[132:133]
	s_mov_b32 m0, s14
	s_nop 0
	global_load_lds_dwordx4 v[244:245], off
	s_waitcnt vmcnt(8)
	s_waitcnt lgkmcnt(0)
	s_barrier
	s_setprio 1
	s_waitcnt lgkmcnt(0)
	v_mfma_f32_16x16x32_bf16 v[126:129], v[146:149], v[178:181], v[126:129]
	v_mfma_f32_16x16x32_bf16 v[122:125], v[154:157], v[178:181], v[122:125]
	v_mfma_f32_16x16x32_bf16 v[110:113], v[146:149], v[186:189], v[110:113]
	v_mfma_f32_16x16x32_bf16 v[106:109], v[154:157], v[186:189], v[106:109]
	v_mfma_f32_16x16x32_bf16 v[94:97], v[146:149], v[204:207], v[94:97]
	v_mfma_f32_16x16x32_bf16 v[90:93], v[154:157], v[204:207], v[90:93]
	v_mfma_f32_16x16x32_bf16 v[78:81], v[146:149], v[214:217], v[78:81]
	v_mfma_f32_16x16x32_bf16 v[74:77], v[154:157], v[214:217], v[74:77]
	v_mfma_f32_16x16x32_bf16 v[126:129], v[150:153], v[182:185], v[126:129]
	v_mfma_f32_16x16x32_bf16 v[122:125], v[158:161], v[182:185], v[122:125]
	v_mfma_f32_16x16x32_bf16 v[110:113], v[150:153], v[200:203], v[110:113]
	v_mfma_f32_16x16x32_bf16 v[106:109], v[158:161], v[200:203], v[106:109]
	v_mfma_f32_16x16x32_bf16 v[94:97], v[150:153], v[208:211], v[94:97]
	v_mfma_f32_16x16x32_bf16 v[90:93], v[158:161], v[208:211], v[90:93]
	v_mfma_f32_16x16x32_bf16 v[78:81], v[150:153], v[232:235], v[78:81]
	v_mfma_f32_16x16x32_bf16 v[74:77], v[158:161], v[232:235], v[74:77]
	s_setprio 0
	s_setprio 1
	v_mfma_f32_16x16x32_bf16 v[118:121], v[162:165], v[178:181], v[118:121]
	v_mfma_f32_16x16x32_bf16 v[114:117], v[170:173], v[178:181], v[114:117]
	v_mfma_f32_16x16x32_bf16 v[102:105], v[162:165], v[186:189], v[102:105]
	v_mfma_f32_16x16x32_bf16 v[98:101], v[170:173], v[186:189], v[98:101]
	v_mfma_f32_16x16x32_bf16 v[86:89], v[162:165], v[204:207], v[86:89]
	v_mfma_f32_16x16x32_bf16 v[82:85], v[170:173], v[204:207], v[82:85]
	v_mfma_f32_16x16x32_bf16 v[70:73], v[162:165], v[214:217], v[70:73]
	v_mfma_f32_16x16x32_bf16 v[66:69], v[170:173], v[214:217], v[66:69]
	v_mfma_f32_16x16x32_bf16 v[118:121], v[166:169], v[182:185], v[118:121]
	v_mfma_f32_16x16x32_bf16 v[114:117], v[174:177], v[182:185], v[114:117]
	v_mfma_f32_16x16x32_bf16 v[102:105], v[166:169], v[200:203], v[102:105]
	v_mfma_f32_16x16x32_bf16 v[98:101], v[174:177], v[200:203], v[98:101]
	v_mfma_f32_16x16x32_bf16 v[86:89], v[166:169], v[208:211], v[86:89]
	v_mfma_f32_16x16x32_bf16 v[82:85], v[174:177], v[208:211], v[82:85]
	v_mfma_f32_16x16x32_bf16 v[70:73], v[166:169], v[232:235], v[70:73]
	v_mfma_f32_16x16x32_bf16 v[66:69], v[174:177], v[232:235], v[66:69]
	s_setprio 0
	s_barrier
; #define PG8_STAGE(bufoff, gbase, voff) do { _Pragma("unroll") for (int _i = 0; _i < 2; ++_i) \
;         __builtin_amdgcn_global_load_lds((const unsigned*)((const char*)(gbase) + (voff)[_i]), (PG8_LAS unsigned*)(lds + (bufoff) + ldsw + _i * 8192), 16, 0, 0); } while (0)
; #define PG8_LDA(dst, b, h) do { _Pragma("unroll") for (int m = 0; m < 4; ++m) _Pragma("unroll") for (int k = 0; k < 2; ++k) dst[m][k] = *(const PG8_LAS bf16x8*)(lds + PG8_SA(b, h) + aoff + m * 2048 + k * 1024); } while (0)
; #define PG8_MMA(ai, bj, At, Bt) do { __builtin_amdgcn_s_setprio(1); _Pragma("unroll") for (int m = 0; m < 4; ++m) _Pragma("unroll") for (int n = 0; n < 2; ++n) _Pragma("unroll") for (int k = 0; k < 2; ++k) \
;         acc[ai][bj][m][n] = __builtin_amdgcn_mfma_f32_16x16x32_bf16(Bt[n][k], At[m][k], acc[ai][bj][m][n], 0, 0, 0); __builtin_amdgcn_s_setprio(0); } while (0)
; #define PG8_WAIT_V(n) asm volatile("s_waitcnt vmcnt(" #n ")" ::: "memory")
; #define PG8_WAIT_L(n) asm volatile("s_waitcnt lgkmcnt(" #n ")" ::: "memory")
; #define PG8_BAR __builtin_amdgcn_s_barrier()
; #define PG8_SCHED __builtin_amdgcn_sched_barrier(0)
; template <class Epi, class Sched, bool ALIGN_EPI = false, bool SP2 = false>
; __device__ __forceinline__ void gemm_phase(PG8_LAS unsigned char* lds, const Gemm g, const Sched& S, const Epi& E, int tid_) {
;     ...
;             PG8_LDA(At, 1, 1); PG8_STAGE(PG8_SB(1, 0), b3, voffB); PG8_STAGE(PG8_SB(1, 1), b3 + hstep, voffB); PG8_STAGE(PG8_SA(1, 0), a3, voffA);
;             PG8_WAIT_V(8); PG8_WAIT_L(0); PG8_BAR; PG8_MMA(1, 0, At, B0); PG8_MMA(1, 1, At, B1); PG8_BAR; PG8_SCHED;
;     ...
;         if constexpr (ALIGN_EPI) { if (wr == 0) PG8_BAR; }
	s_add_i32 s21, s21, s9
	v_lshl_add_u64 v[140:141], v[140:141], 0, s[28:29]
	s_mov_b32 m0, s21
	ds_read_b128 v[178:181], v145 offset:49152
	ds_read_b128 v[182:185], v145 offset:50176
	ds_read_b128 v[186:189], v145 offset:51200
	ds_read_b128 v[200:203], v145 offset:52224
	ds_read_b128 v[204:207], v145 offset:53248
	ds_read_b128 v[208:211], v145 offset:54272
	ds_read_b128 v[214:217], v145 offset:55296
	ds_read_b128 v[232:235], v145 offset:56320
	global_load_lds_dwordx4 v[140:141], off
	v_lshl_add_u64 v[140:141], v[190:191], 0, s[28:29]
	s_add_i32 m0, s21, 0x2000
	s_add_i32 s21, s92, s9
	global_load_lds_dwordx4 v[140:141], off
	v_lshl_add_u64 v[140:141], v[236:237], 0, s[28:29]
	s_mov_b32 m0, s21
	s_nop 0
	global_load_lds_dwordx4 v[140:141], off
	s_add_i32 m0, s21, 0x2000
	v_lshl_add_u64 v[140:141], v[238:239], 0, s[28:29]
	global_load_lds_dwordx4 v[140:141], off
	v_lshl_add_u64 v[140:141], v[240:241], 0, s[28:29]
	s_mov_b32 m0, s37
	s_nop 0
	global_load_lds_dwordx4 v[140:141], off
	v_lshl_add_u64 v[140:141], v[242:243], 0, s[28:29]
	s_mov_b32 m0, s69
	s_nop 0
	global_load_lds_dwordx4 v[140:141], off
	s_waitcnt vmcnt(8)
	s_waitcnt lgkmcnt(0)
	s_barrier
	s_setprio 1
	s_waitcnt lgkmcnt(0)
	v_mfma_f32_16x16x32_bf16 v[62:65], v[146:149], v[178:181], v[62:65]
	v_mfma_f32_16x16x32_bf16 v[58:61], v[154:157], v[178:181], v[58:61]
	v_mfma_f32_16x16x32_bf16 v[46:49], v[146:149], v[186:189], v[46:49]
	v_mfma_f32_16x16x32_bf16 v[42:45], v[154:157], v[186:189], v[42:45]
	v_mfma_f32_16x16x32_bf16 v[30:33], v[146:149], v[204:207], v[30:33]
	v_mfma_f32_16x16x32_bf16 v[26:29], v[154:157], v[204:207], v[26:29]
	v_mfma_f32_16x16x32_bf16 v[14:17], v[146:149], v[214:217], v[14:17]
	v_mfma_f32_16x16x32_bf16 v[10:13], v[154:157], v[214:217], v[10:13]
	v_mfma_f32_16x16x32_bf16 v[62:65], v[150:153], v[182:185], v[62:65]
	v_mfma_f32_16x16x32_bf16 v[58:61], v[158:161], v[182:185], v[58:61]
	v_mfma_f32_16x16x32_bf16 v[46:49], v[150:153], v[200:203], v[46:49]
	v_mfma_f32_16x16x32_bf16 v[42:45], v[158:161], v[200:203], v[42:45]
	v_mfma_f32_16x16x32_bf16 v[30:33], v[150:153], v[208:211], v[30:33]
	v_mfma_f32_16x16x32_bf16 v[26:29], v[158:161], v[208:211], v[26:29]
	v_mfma_f32_16x16x32_bf16 v[14:17], v[150:153], v[232:235], v[14:17]
	v_mfma_f32_16x16x32_bf16 v[10:13], v[158:161], v[232:235], v[10:13]
	s_setprio 0
	s_setprio 1
	v_mfma_f32_16x16x32_bf16 v[54:57], v[162:165], v[178:181], v[54:57]
	v_mfma_f32_16x16x32_bf16 v[50:53], v[170:173], v[178:181], v[50:53]
	v_mfma_f32_16x16x32_bf16 v[38:41], v[162:165], v[186:189], v[38:41]
	v_mfma_f32_16x16x32_bf16 v[34:37], v[170:173], v[186:189], v[34:37]
	v_mfma_f32_16x16x32_bf16 v[22:25], v[162:165], v[204:207], v[22:25]
	v_mfma_f32_16x16x32_bf16 v[18:21], v[170:173], v[204:207], v[18:21]
	v_mfma_f32_16x16x32_bf16 v[6:9], v[162:165], v[214:217], v[6:9]
	v_mfma_f32_16x16x32_bf16 v[2:5], v[170:173], v[214:217], v[2:5]
	v_mfma_f32_16x16x32_bf16 v[54:57], v[166:169], v[182:185], v[54:57]
	v_mfma_f32_16x16x32_bf16 v[50:53], v[174:177], v[182:185], v[50:53]
	v_mfma_f32_16x16x32_bf16 v[38:41], v[166:169], v[200:203], v[38:41]
	v_mfma_f32_16x16x32_bf16 v[34:37], v[174:177], v[200:203], v[34:37]
	v_mfma_f32_16x16x32_bf16 v[22:25], v[166:169], v[208:211], v[22:25]
	v_mfma_f32_16x16x32_bf16 v[18:21], v[174:177], v[208:211], v[18:21]
	v_mfma_f32_16x16x32_bf16 v[6:9], v[166:169], v[232:235], v[6:9]
	v_mfma_f32_16x16x32_bf16 v[2:5], v[174:177], v[232:235], v[2:5]
	s_setprio 0
	s_barrier
	s_add_u32 s80, s80, 0x100
	s_addc_u32 s81, s81, 0
	s_add_u32 s70, s70, 0x100
	s_addc_u32 s71, s71, 0
	s_cmp_ge_i32 s91, s90
	s_mov_b32 s64, s91
	s_cbranch_scc0 .LBB0_226
	s_and_b64 vcc, exec, s[50:51]
	s_cbranch_vccz .LBB0_229
	s_barrier

; #define PG8_STAGE(bufoff, gbase, voff) do { _Pragma("unroll") for (int _i = 0; _i < 2; ++_i) \
;         __builtin_amdgcn_global_load_lds((const unsigned*)((const char*)(gbase) + (voff)[_i]), (PG8_LAS unsigned*)(lds + (bufoff) + ldsw + _i * 8192), 16, 0, 0); } while (0)
; #define PG8_LDA(dst, b, h) do { _Pragma("unroll") for (int m = 0; m < 4; ++m) _Pragma("unroll") for (int k = 0; k < 2; ++k) dst[m][k] = *(const PG8_LAS bf16x8*)(lds + PG8_SA(b, h) + aoff + m * 2048 + k * 1024); } while (0)
; #define PG8_LDB(dst, b, h) do { _Pragma("unroll") for (int n = 0; n < 2; ++n) _Pragma("unroll") for (int k = 0; k < 2; ++k) dst[n][k] = *(const PG8_LAS bf16x8*)(lds + PG8_SB(b, h) + boff + n * 2048 + k * 1024); } while (0)
; #define PG8_MMA(ai, bj, At, Bt) do { __builtin_amdgcn_s_setprio(1); _Pragma("unroll") for (int m = 0; m < 4; ++m) _Pragma("unroll") for (int n = 0; n < 2; ++n) _Pragma("unroll") for (int k = 0; k < 2; ++k) \
;         acc[ai][bj][m][n] = __builtin_amdgcn_mfma_f32_16x16x32_bf16(Bt[n][k], At[m][k], acc[ai][bj][m][n], 0, 0, 0); __builtin_amdgcn_s_setprio(0); } while (0)
; #define PG8_WAIT_V(n) asm volatile("s_waitcnt vmcnt(" #n ")" ::: "memory")
; #define PG8_WAIT_L(n) asm volatile("s_waitcnt lgkmcnt(" #n ")" ::: "memory")
; template <class Epi, class Sched, bool ALIGN_EPI = false, bool SP2 = false>
; __device__ __forceinline__ void gemm_phase(PG8_LAS unsigned char* lds, const Gemm g, const Sched& S, const Epi& E, int tid_) {
;     ...
;             const bool last = (t == nt - 2);
;             const char* a1 = cA + (size_t)(t + 1) * kstep;
;             const char* a2 = last ? nA : cA + (size_t)(t + 2) * kstep; const char* b2 = last ? nB : cB + (size_t)(t + 2) * kstep;
;             const char* a3 = a2 + kstep; const char* b3 = b2 + kstep;
;             if (last && has_next) S.a_ready(nxt);
;             if constexpr (SP2) {
;             PG8_LDB(B0, 0, 0); PG8_LDB(B1, 0, 1); PG8_SCHED; PG8_LDA(At, 0, 0); PG8_STAGE(PG8_SA(1, 1), a1 + hstep, voffA);
;             PG8_WAIT_V(8); PG8_WAIT_L(0); PG8_BAR; PG8_MMA(0, 0, At, B0); PG8_MMA(0, 1, At, B1); PG8_BAR; PG8_SCHED;
;             PG8_LDA(At, 0, 1); PG8_STAGE(PG8_SB(0, 0), b2, voffB); PG8_STAGE(PG8_SB(0, 1), b2 + hstep, voffB); PG8_STAGE(PG8_SA(0, 0), a2, voffA);
;             PG8_WAIT_V(8); PG8_WAIT_L(0); PG8_BAR; PG8_MMA(1, 0, At, B0); PG8_MMA(1, 1, At, B1); PG8_BAR; PG8_SCHED;
.LBB0_438:
	v_add_u32_e32 v142, 0x10000, v199
	v_add_u32_e32 v168, 0x14000, v199
	ds_read_b128 v[130:133], v142
	ds_read_b128 v[134:137], v142 offset:1024
	ds_read_b128 v[138:141], v142 offset:2048
	ds_read_b128 v[142:145], v142 offset:3072
	ds_read_b128 v[146:149], v168
	ds_read_b128 v[150:153], v168 offset:1024
	ds_read_b128 v[154:157], v168 offset:2048
	ds_read_b128 v[168:171], v168 offset:3072
	s_add_i32 s74, s64, 2
	s_add_u32 s13, vcc_lo, 0x80
	s_addc_u32 s14, vcc_hi, 0
	s_add_i32 s75, 0, 0x10000
	s_cmp_eq_u32 s73, s64
	s_cselect_b32 s65, s23, s14
	s_cselect_b32 s64, s22, s13
	s_cselect_b32 s91, s61, s81
	s_cselect_b32 s90, s60, s80
	s_add_i32 s13, 0, 0x14000
	v_lshl_add_u64 v[232:233], vcc, 0, v[166:167]
	s_add_i32 m0, s93, 0xc000
	ds_read_b128 v[172:175], v210
	ds_read_b128 v[176:179], v210 offset:1024
	ds_read_b128 v[180:183], v210 offset:2048
	ds_read_b128 v[184:187], v210 offset:3072
	ds_read_b128 v[188:191], v210 offset:4096
	ds_read_b128 v[200:203], v210 offset:5120
	ds_read_b128 v[204:207], v210 offset:6144
	ds_read_b128 v[214:217], v210 offset:7168
	global_load_lds_dwordx4 v[232:233], off
	s_add_i32 m0, s93, 0xe000
	v_lshl_add_u64 v[232:233], vcc, 0, v[164:165]
	global_load_lds_dwordx4 v[232:233], off
	s_waitcnt vmcnt(8)
	s_waitcnt lgkmcnt(0)
	s_barrier
	s_setprio 1
	s_waitcnt lgkmcnt(0)
	v_mfma_f32_16x16x32_bf16 v[126:129], v[130:133], v[172:175], v[126:129]
	v_mfma_f32_16x16x32_bf16 v[122:125], v[138:141], v[172:175], v[122:125]
	v_mfma_f32_16x16x32_bf16 v[110:113], v[130:133], v[180:183], v[110:113]
	v_mfma_f32_16x16x32_bf16 v[106:109], v[138:141], v[180:183], v[106:109]
	v_mfma_f32_16x16x32_bf16 v[94:97], v[130:133], v[188:191], v[94:97]
	v_mfma_f32_16x16x32_bf16 v[90:93], v[138:141], v[188:191], v[90:93]
	v_mfma_f32_16x16x32_bf16 v[78:81], v[130:133], v[204:207], v[78:81]
	v_mfma_f32_16x16x32_bf16 v[74:77], v[138:141], v[204:207], v[74:77]
	v_mfma_f32_16x16x32_bf16 v[126:129], v[134:137], v[176:179], v[126:129]
	v_mfma_f32_16x16x32_bf16 v[122:125], v[142:145], v[176:179], v[122:125]
	v_mfma_f32_16x16x32_bf16 v[110:113], v[134:137], v[184:187], v[110:113]
	v_mfma_f32_16x16x32_bf16 v[106:109], v[142:145], v[184:187], v[106:109]
	v_mfma_f32_16x16x32_bf16 v[94:97], v[134:137], v[200:203], v[94:97]
	v_mfma_f32_16x16x32_bf16 v[90:93], v[142:145], v[200:203], v[90:93]
	v_mfma_f32_16x16x32_bf16 v[78:81], v[134:137], v[214:217], v[78:81]
	v_mfma_f32_16x16x32_bf16 v[74:77], v[142:145], v[214:217], v[74:77]
	s_setprio 0
	s_setprio 1
	v_mfma_f32_16x16x32_bf16 v[118:121], v[146:149], v[172:175], v[118:121]
	v_mfma_f32_16x16x32_bf16 v[114:117], v[154:157], v[172:175], v[114:117]
	v_mfma_f32_16x16x32_bf16 v[102:105], v[146:149], v[180:183], v[102:105]
	v_mfma_f32_16x16x32_bf16 v[98:101], v[154:157], v[180:183], v[98:101]
	v_mfma_f32_16x16x32_bf16 v[86:89], v[146:149], v[188:191], v[86:89]
	v_mfma_f32_16x16x32_bf16 v[82:85], v[154:157], v[188:191], v[82:85]
	v_mfma_f32_16x16x32_bf16 v[70:73], v[146:149], v[204:207], v[70:73]
	v_mfma_f32_16x16x32_bf16 v[66:69], v[154:157], v[204:207], v[66:69]
	v_mfma_f32_16x16x32_bf16 v[118:121], v[150:153], v[176:179], v[118:121]
	v_mfma_f32_16x16x32_bf16 v[114:117], v[168:171], v[176:179], v[114:117]
	v_mfma_f32_16x16x32_bf16 v[102:105], v[150:153], v[184:187], v[102:105]
	v_mfma_f32_16x16x32_bf16 v[98:101], v[168:171], v[184:187], v[98:101]
	v_mfma_f32_16x16x32_bf16 v[86:89], v[150:153], v[200:203], v[86:89]
	v_mfma_f32_16x16x32_bf16 v[82:85], v[168:171], v[200:203], v[82:85]
	v_mfma_f32_16x16x32_bf16 v[70:73], v[150:153], v[214:217], v[70:73]
	v_mfma_f32_16x16x32_bf16 v[66:69], v[168:171], v[214:217], v[66:69]
	s_setprio 0
	s_barrier
	s_add_i32 s14, s75, s92
	v_lshl_add_u64 v[232:233], s[90:91], 0, v[0:1]
	s_mov_b32 m0, s14
	ds_read_b128 v[172:175], v210 offset:16384
	ds_read_b128 v[176:179], v210 offset:17408
	ds_read_b128 v[180:183], v210 offset:18432
	ds_read_b128 v[184:187], v210 offset:19456
	ds_read_b128 v[188:191], v210 offset:20480
	ds_read_b128 v[200:203], v210 offset:21504
	ds_read_b128 v[204:207], v210 offset:22528
	ds_read_b128 v[214:217], v210 offset:23552
	global_load_lds_dwordx4 v[232:233], off
	s_add_i32 m0, s14, 0x2000
	v_lshl_add_u64 v[234:235], s[90:91], 0, v[162:163]
	s_add_u32 s90, s90, s50
	s_addc_u32 s91, s91, s51
	s_add_i32 s13, s13, s92
	global_load_lds_dwordx4 v[234:235], off
	v_lshl_add_u64 v[236:237], s[90:91], 0, v[0:1]
	s_mov_b32 m0, s13
	v_lshl_add_u64 v[238:239], s[90:91], 0, v[162:163]
	global_load_lds_dwordx4 v[236:237], off
	s_add_i32 m0, s13, 0x2000
	v_lshl_add_u64 v[240:241], s[64:65], 0, v[158:159]
	global_load_lds_dwordx4 v[238:239], off
	s_mov_b32 m0, s93
	v_lshl_add_u64 v[242:243], s[64:65], 0, v[160:161]
	global_load_lds_dwordx4 v[240:241], off
	s_mov_b32 m0, s94
	s_nop 0
	global_load_lds_dwordx4 v[242:243], off
	s_waitcnt vmcnt(8)
	s_waitcnt lgkmcnt(0)
	s_barrier
; #define PG8_STAGE(bufoff, gbase, voff) do { _Pragma("unroll") for (int _i = 0; _i < 2; ++_i) \
;         __builtin_amdgcn_global_load_lds((const unsigned*)((const char*)(gbase) + (voff)[_i]), (PG8_LAS unsigned*)(lds + (bufoff) + ldsw + _i * 8192), 16, 0, 0); } while (0)
; #define PG8_LDA(dst, b, h) do { _Pragma("unroll") for (int m = 0; m < 4; ++m) _Pragma("unroll") for (int k = 0; k < 2; ++k) dst[m][k] = *(const PG8_LAS bf16x8*)(lds + PG8_SA(b, h) + aoff + m * 2048 + k * 1024); } while (0)
; #define PG8_LDB(dst, b, h) do { _Pragma("unroll") for (int n = 0; n < 2; ++n) _Pragma("unroll") for (int k = 0; k < 2; ++k) dst[n][k] = *(const PG8_LAS bf16x8*)(lds + PG8_SB(b, h) + boff + n * 2048 + k * 1024); } while (0)
; #define PG8_MMA(ai, bj, At, Bt) do { __builtin_amdgcn_s_setprio(1); _Pragma("unroll") for (int m = 0; m < 4; ++m) _Pragma("unroll") for (int n = 0; n < 2; ++n) _Pragma("unroll") for (int k = 0; k < 2; ++k) \
;         acc[ai][bj][m][n] = __builtin_amdgcn_mfma_f32_16x16x32_bf16(Bt[n][k], At[m][k], acc[ai][bj][m][n], 0, 0, 0); __builtin_amdgcn_s_setprio(0); } while (0)
; #define PG8_WAIT_V(n) asm volatile("s_waitcnt vmcnt(" #n ")" ::: "memory")
; #define PG8_WAIT_L(n) asm volatile("s_waitcnt lgkmcnt(" #n ")" ::: "memory")
; #define PG8_BAR __builtin_amdgcn_s_barrier()
; #define PG8_SCHED __builtin_amdgcn_sched_barrier(0)
; template <class Epi, class Sched, bool ALIGN_EPI = false, bool SP2 = false>
; __device__ __forceinline__ void gemm_phase(PG8_LAS unsigned char* lds, const Gemm g, const Sched& S, const Epi& E, int tid_) {
;     ...
;             PG8_WAIT_V(8); PG8_WAIT_L(0); PG8_BAR; PG8_MMA(1, 0, At, B0); PG8_MMA(1, 1, At, B1); PG8_BAR; PG8_SCHED;
;             PG8_LDB(B0, 1, 0); PG8_LDB(B1, 1, 1); PG8_SCHED; PG8_LDA(At, 1, 0); PG8_STAGE(PG8_SA(0, 1), a2 + hstep, voffA);
;             PG8_WAIT_V(8); PG8_WAIT_L(0); PG8_BAR; PG8_MMA(0, 0, At, B0); PG8_MMA(0, 1, At, B1); PG8_BAR; PG8_SCHED;
	s_setprio 1
	s_waitcnt lgkmcnt(0)
	v_mfma_f32_16x16x32_bf16 v[62:65], v[130:133], v[172:175], v[62:65]
	v_mfma_f32_16x16x32_bf16 v[58:61], v[138:141], v[172:175], v[58:61]
	v_mfma_f32_16x16x32_bf16 v[46:49], v[130:133], v[180:183], v[46:49]
	v_mfma_f32_16x16x32_bf16 v[42:45], v[138:141], v[180:183], v[42:45]
	v_mfma_f32_16x16x32_bf16 v[30:33], v[130:133], v[188:191], v[30:33]
	v_mfma_f32_16x16x32_bf16 v[26:29], v[138:141], v[188:191], v[26:29]
	v_mfma_f32_16x16x32_bf16 v[14:17], v[130:133], v[204:207], v[14:17]
	v_mfma_f32_16x16x32_bf16 v[10:13], v[138:141], v[204:207], v[10:13]
	v_mfma_f32_16x16x32_bf16 v[62:65], v[134:137], v[176:179], v[62:65]
	v_mfma_f32_16x16x32_bf16 v[58:61], v[142:145], v[176:179], v[58:61]
	v_mfma_f32_16x16x32_bf16 v[46:49], v[134:137], v[184:187], v[46:49]
	v_mfma_f32_16x16x32_bf16 v[42:45], v[142:145], v[184:187], v[42:45]
	v_mfma_f32_16x16x32_bf16 v[30:33], v[134:137], v[200:203], v[30:33]
	v_mfma_f32_16x16x32_bf16 v[26:29], v[142:145], v[200:203], v[26:29]
	v_mfma_f32_16x16x32_bf16 v[14:17], v[134:137], v[214:217], v[14:17]
	v_mfma_f32_16x16x32_bf16 v[10:13], v[142:145], v[214:217], v[10:13]
	s_setprio 0
	s_setprio 1
	v_mfma_f32_16x16x32_bf16 v[54:57], v[146:149], v[172:175], v[54:57]
	v_mfma_f32_16x16x32_bf16 v[50:53], v[154:157], v[172:175], v[50:53]
	v_mfma_f32_16x16x32_bf16 v[38:41], v[146:149], v[180:183], v[38:41]
	v_mfma_f32_16x16x32_bf16 v[34:37], v[154:157], v[180:183], v[34:37]
	v_mfma_f32_16x16x32_bf16 v[22:25], v[146:149], v[188:191], v[22:25]
	v_mfma_f32_16x16x32_bf16 v[18:21], v[154:157], v[188:191], v[18:21]
	v_mfma_f32_16x16x32_bf16 v[6:9], v[146:149], v[204:207], v[6:9]
	v_mfma_f32_16x16x32_bf16 v[2:5], v[154:157], v[204:207], v[2:5]
	v_mfma_f32_16x16x32_bf16 v[54:57], v[150:153], v[176:179], v[54:57]
	v_mfma_f32_16x16x32_bf16 v[50:53], v[168:171], v[176:179], v[50:53]
	v_mfma_f32_16x16x32_bf16 v[38:41], v[150:153], v[184:187], v[38:41]
	v_mfma_f32_16x16x32_bf16 v[34:37], v[168:171], v[184:187], v[34:37]
	v_mfma_f32_16x16x32_bf16 v[22:25], v[150:153], v[200:203], v[22:25]
	v_mfma_f32_16x16x32_bf16 v[18:21], v[168:171], v[200:203], v[18:21]
	v_mfma_f32_16x16x32_bf16 v[6:9], v[150:153], v[214:217], v[6:9]
	v_mfma_f32_16x16x32_bf16 v[2:5], v[168:171], v[214:217], v[2:5]
	s_setprio 0
	s_barrier
	s_add_i32 s13, 0, 0x18000
	s_add_i32 s14, 0, 0x1c000
	v_add_u32_e32 v142, s13, v199
	v_add_u32_e32 v168, s14, v199
	ds_read_b128 v[130:133], v142
	ds_read_b128 v[134:137], v142 offset:1024
	ds_read_b128 v[138:141], v142 offset:2048
	ds_read_b128 v[142:145], v142 offset:3072
	ds_read_b128 v[146:149], v168
	ds_read_b128 v[150:153], v168 offset:1024
	ds_read_b128 v[154:157], v168 offset:2048
	ds_read_b128 v[168:171], v168 offset:3072
	s_add_u32 s64, s64, s50
	s_addc_u32 s65, s65, s51
	s_mov_b32 m0, s95
	v_lshl_add_u64 v[244:245], s[64:65], 0, v[158:159]
	ds_read_b128 v[172:175], v210 offset:32768
	ds_read_b128 v[176:179], v210 offset:33792
	ds_read_b128 v[180:183], v210 offset:34816
	ds_read_b128 v[184:187], v210 offset:35840
	ds_read_b128 v[188:191], v210 offset:36864
	ds_read_b128 v[200:203], v210 offset:37888
	ds_read_b128 v[204:207], v210 offset:38912
	ds_read_b128 v[214:217], v210 offset:39936
	global_load_lds_dwordx4 v[244:245], off
	v_lshl_add_u64 v[244:245], s[64:65], 0, v[160:161]
	s_mov_b32 m0, s96
	s_nop 0
	global_load_lds_dwordx4 v[244:245], off
	s_waitcnt vmcnt(8)
	s_waitcnt lgkmcnt(0)
	s_barrier
	s_setprio 1
	s_waitcnt lgkmcnt(0)
	v_mfma_f32_16x16x32_bf16 v[126:129], v[130:133], v[172:175], v[126:129]
	v_mfma_f32_16x16x32_bf16 v[122:125], v[138:141], v[172:175], v[122:125]
	v_mfma_f32_16x16x32_bf16 v[110:113], v[130:133], v[180:183], v[110:113]
	v_mfma_f32_16x16x32_bf16 v[106:109], v[138:141], v[180:183], v[106:109]
	v_mfma_f32_16x16x32_bf16 v[94:97], v[130:133], v[188:191], v[94:97]
	v_mfma_f32_16x16x32_bf16 v[90:93], v[138:141], v[188:191], v[90:93]
	v_mfma_f32_16x16x32_bf16 v[78:81], v[130:133], v[204:207], v[78:81]
	v_mfma_f32_16x16x32_bf16 v[74:77], v[138:141], v[204:207], v[74:77]
	v_mfma_f32_16x16x32_bf16 v[126:129], v[134:137], v[176:179], v[126:129]
	v_mfma_f32_16x16x32_bf16 v[122:125], v[142:145], v[176:179], v[122:125]
	v_mfma_f32_16x16x32_bf16 v[110:113], v[134:137], v[184:187], v[110:113]
	v_mfma_f32_16x16x32_bf16 v[106:109], v[142:145], v[184:187], v[106:109]
	v_mfma_f32_16x16x32_bf16 v[94:97], v[134:137], v[200:203], v[94:97]
	v_mfma_f32_16x16x32_bf16 v[90:93], v[142:145], v[200:203], v[90:93]
	v_mfma_f32_16x16x32_bf16 v[78:81], v[134:137], v[214:217], v[78:81]
	v_mfma_f32_16x16x32_bf16 v[74:77], v[142:145], v[214:217], v[74:77]
	s_setprio 0
	s_setprio 1
	v_mfma_f32_16x16x32_bf16 v[118:121], v[146:149], v[172:175], v[118:121]
	v_mfma_f32_16x16x32_bf16 v[114:117], v[154:157], v[172:175], v[114:117]
	v_mfma_f32_16x16x32_bf16 v[102:105], v[146:149], v[180:183], v[102:105]
	v_mfma_f32_16x16x32_bf16 v[98:101], v[154:157], v[180:183], v[98:101]
	v_mfma_f32_16x16x32_bf16 v[86:89], v[146:149], v[188:191], v[86:89]
	v_mfma_f32_16x16x32_bf16 v[82:85], v[154:157], v[188:191], v[82:85]
	v_mfma_f32_16x16x32_bf16 v[70:73], v[146:149], v[204:207], v[70:73]
	v_mfma_f32_16x16x32_bf16 v[66:69], v[154:157], v[204:207], v[66:69]
	v_mfma_f32_16x16x32_bf16 v[118:121], v[150:153], v[176:179], v[118:121]
	v_mfma_f32_16x16x32_bf16 v[114:117], v[168:171], v[176:179], v[114:117]
	v_mfma_f32_16x16x32_bf16 v[102:105], v[150:153], v[184:187], v[102:105]
	v_mfma_f32_16x16x32_bf16 v[98:101], v[168:171], v[184:187], v[98:101]
	v_mfma_f32_16x16x32_bf16 v[86:89], v[150:153], v[200:203], v[86:89]
	v_mfma_f32_16x16x32_bf16 v[82:85], v[168:171], v[200:203], v[82:85]
	v_mfma_f32_16x16x32_bf16 v[70:73], v[150:153], v[214:217], v[70:73]
	v_mfma_f32_16x16x32_bf16 v[66:69], v[168:171], v[214:217], v[66:69]
	s_setprio 0
	s_barrier
; #define PG8_STAGE(bufoff, gbase, voff) do { _Pragma("unroll") for (int _i = 0; _i < 2; ++_i) \
;         __builtin_amdgcn_global_load_lds((const unsigned*)((const char*)(gbase) + (voff)[_i]), (PG8_LAS unsigned*)(lds + (bufoff) + ldsw + _i * 8192), 16, 0, 0); } while (0)
; #define PG8_LDA(dst, b, h) do { _Pragma("unroll") for (int m = 0; m < 4; ++m) _Pragma("unroll") for (int k = 0; k < 2; ++k) dst[m][k] = *(const PG8_LAS bf16x8*)(lds + PG8_SA(b, h) + aoff + m * 2048 + k * 1024); } while (0)
; #define PG8_MMA(ai, bj, At, Bt) do { __builtin_amdgcn_s_setprio(1); _Pragma("unroll") for (int m = 0; m < 4; ++m) _Pragma("unroll") for (int n = 0; n < 2; ++n) _Pragma("unroll") for (int k = 0; k < 2; ++k) \
;         acc[ai][bj][m][n] = __builtin_amdgcn_mfma_f32_16x16x32_bf16(Bt[n][k], At[m][k], acc[ai][bj][m][n], 0, 0, 0); __builtin_amdgcn_s_setprio(0); } while (0)
; #define PG8_WAIT_V(n) asm volatile("s_waitcnt vmcnt(" #n ")" ::: "memory")
; #define PG8_WAIT_L(n) asm volatile("s_waitcnt lgkmcnt(" #n ")" ::: "memory")
; #define PG8_BAR __builtin_amdgcn_s_barrier()
; #define PG8_SCHED __builtin_amdgcn_sched_barrier(0)
; template <class Epi, class Sched, bool ALIGN_EPI = false, bool SP2 = false>
; __device__ __forceinline__ void gemm_phase(PG8_LAS unsigned char* lds, const Gemm g, const Sched& S, const Epi& E, int tid_) {
;     ...
;             PG8_LDA(At, 1, 1); PG8_STAGE(PG8_SB(1, 0), b3, voffB); PG8_STAGE(PG8_SB(1, 1), b3 + hstep, voffB); PG8_STAGE(PG8_SA(1, 0), a3, voffA);
;             PG8_WAIT_V(8); PG8_WAIT_L(0); PG8_BAR; PG8_MMA(1, 0, At, B0); PG8_MMA(1, 1, At, B1); PG8_BAR; PG8_SCHED;
;     ...
;         if constexpr (ALIGN_EPI) { if (wr == 0) PG8_BAR; }
	s_add_i32 s13, s13, s92
	v_lshl_add_u64 v[232:233], v[232:233], 0, s[28:29]
	s_mov_b32 m0, s13
	ds_read_b128 v[172:175], v210 offset:49152
	ds_read_b128 v[176:179], v210 offset:50176
	ds_read_b128 v[180:183], v210 offset:51200
	ds_read_b128 v[184:187], v210 offset:52224
	ds_read_b128 v[188:191], v210 offset:53248
	ds_read_b128 v[200:203], v210 offset:54272
	ds_read_b128 v[204:207], v210 offset:55296
	ds_read_b128 v[214:217], v210 offset:56320
	global_load_lds_dwordx4 v[232:233], off
	v_lshl_add_u64 v[232:233], v[234:235], 0, s[28:29]
	s_add_i32 m0, s13, 0x2000
	s_add_i32 s13, s14, s92
	global_load_lds_dwordx4 v[232:233], off
	v_lshl_add_u64 v[232:233], v[236:237], 0, s[28:29]
	s_mov_b32 m0, s13
	s_nop 0
	global_load_lds_dwordx4 v[232:233], off
	s_add_i32 m0, s13, 0x2000
	v_lshl_add_u64 v[232:233], v[238:239], 0, s[28:29]
	global_load_lds_dwordx4 v[232:233], off
	v_lshl_add_u64 v[232:233], v[240:241], 0, s[28:29]
	s_mov_b32 m0, s97
	s_nop 0
	global_load_lds_dwordx4 v[232:233], off
	v_lshl_add_u64 v[232:233], v[242:243], 0, s[28:29]
	s_mov_b32 m0, s98
	s_nop 0
	global_load_lds_dwordx4 v[232:233], off
	s_waitcnt vmcnt(8)
	s_waitcnt lgkmcnt(0)
	s_barrier
	s_setprio 1
	s_waitcnt lgkmcnt(0)
	v_mfma_f32_16x16x32_bf16 v[62:65], v[130:133], v[172:175], v[62:65]
	v_mfma_f32_16x16x32_bf16 v[58:61], v[138:141], v[172:175], v[58:61]
	v_mfma_f32_16x16x32_bf16 v[46:49], v[130:133], v[180:183], v[46:49]
	v_mfma_f32_16x16x32_bf16 v[42:45], v[138:141], v[180:183], v[42:45]
	v_mfma_f32_16x16x32_bf16 v[30:33], v[130:133], v[188:191], v[30:33]
	v_mfma_f32_16x16x32_bf16 v[26:29], v[138:141], v[188:191], v[26:29]
	v_mfma_f32_16x16x32_bf16 v[14:17], v[130:133], v[204:207], v[14:17]
	v_mfma_f32_16x16x32_bf16 v[10:13], v[138:141], v[204:207], v[10:13]
	v_mfma_f32_16x16x32_bf16 v[62:65], v[134:137], v[176:179], v[62:65]
	v_mfma_f32_16x16x32_bf16 v[58:61], v[142:145], v[176:179], v[58:61]
	v_mfma_f32_16x16x32_bf16 v[46:49], v[134:137], v[184:187], v[46:49]
	v_mfma_f32_16x16x32_bf16 v[42:45], v[142:145], v[184:187], v[42:45]
	v_mfma_f32_16x16x32_bf16 v[30:33], v[134:137], v[200:203], v[30:33]
	v_mfma_f32_16x16x32_bf16 v[26:29], v[142:145], v[200:203], v[26:29]
	v_mfma_f32_16x16x32_bf16 v[14:17], v[134:137], v[214:217], v[14:17]
	v_mfma_f32_16x16x32_bf16 v[10:13], v[142:145], v[214:217], v[10:13]
	s_setprio 0
	s_setprio 1
	v_mfma_f32_16x16x32_bf16 v[54:57], v[146:149], v[172:175], v[54:57]
	v_mfma_f32_16x16x32_bf16 v[50:53], v[154:157], v[172:175], v[50:53]
	v_mfma_f32_16x16x32_bf16 v[38:41], v[146:149], v[180:183], v[38:41]
	v_mfma_f32_16x16x32_bf16 v[34:37], v[154:157], v[180:183], v[34:37]
	v_mfma_f32_16x16x32_bf16 v[22:25], v[146:149], v[188:191], v[22:25]
	v_mfma_f32_16x16x32_bf16 v[18:21], v[154:157], v[188:191], v[18:21]
	v_mfma_f32_16x16x32_bf16 v[6:9], v[146:149], v[204:207], v[6:9]
	v_mfma_f32_16x16x32_bf16 v[2:5], v[154:157], v[204:207], v[2:5]
	v_mfma_f32_16x16x32_bf16 v[54:57], v[150:153], v[176:179], v[54:57]
	v_mfma_f32_16x16x32_bf16 v[50:53], v[168:171], v[176:179], v[50:53]
	v_mfma_f32_16x16x32_bf16 v[38:41], v[150:153], v[184:187], v[38:41]
	v_mfma_f32_16x16x32_bf16 v[34:37], v[168:171], v[184:187], v[34:37]
	v_mfma_f32_16x16x32_bf16 v[22:25], v[150:153], v[200:203], v[22:25]
	v_mfma_f32_16x16x32_bf16 v[18:21], v[168:171], v[200:203], v[18:21]
	v_mfma_f32_16x16x32_bf16 v[6:9], v[150:153], v[214:217], v[6:9]
	v_mfma_f32_16x16x32_bf16 v[2:5], v[168:171], v[214:217], v[2:5]
	s_setprio 0
	s_barrier
	s_add_u32 s80, s80, 0x100
	s_addc_u32 s81, s81, 0
	s_add_u32 vcc_lo, vcc_lo, 0x100
	s_addc_u32 vcc_hi, vcc_hi, 0
	s_cmp_ge_i32 s74, s86
	s_mov_b32 s64, s74
	s_cbranch_scc0 .LBB0_438
	s_movk_i32 s90, 0x7ff
	s_movk_i32 s91, 0x80
	s_and_b64 vcc, exec, s[56:57]
	s_cbranch_vccz .LBB0_441

; #define PG8_STAGE(bufoff, gbase, voff) do { _Pragma("unroll") for (int _i = 0; _i < 2; ++_i) \
;         __builtin_amdgcn_global_load_lds((const unsigned*)((const char*)(gbase) + (voff)[_i]), (PG8_LAS unsigned*)(lds + (bufoff) + ldsw + _i * 8192), 16, 0, 0); } while (0)
; #define PG8_LDA(dst, b, h) do { _Pragma("unroll") for (int m = 0; m < 4; ++m) _Pragma("unroll") for (int k = 0; k < 2; ++k) dst[m][k] = *(const PG8_LAS bf16x8*)(lds + PG8_SA(b, h) + aoff + m * 2048 + k * 1024); } while (0)
; #define PG8_LDB(dst, b, h) do { _Pragma("unroll") for (int n = 0; n < 2; ++n) _Pragma("unroll") for (int k = 0; k < 2; ++k) dst[n][k] = *(const PG8_LAS bf16x8*)(lds + PG8_SB(b, h) + boff + n * 2048 + k * 1024); } while (0)
; #define PG8_MMA(ai, bj, At, Bt) do { __builtin_amdgcn_s_setprio(1); _Pragma("unroll") for (int m = 0; m < 4; ++m) _Pragma("unroll") for (int n = 0; n < 2; ++n) _Pragma("unroll") for (int k = 0; k < 2; ++k) \
;         acc[ai][bj][m][n] = __builtin_amdgcn_mfma_f32_16x16x32_bf16(Bt[n][k], At[m][k], acc[ai][bj][m][n], 0, 0, 0); __builtin_amdgcn_s_setprio(0); } while (0)
; #define PG8_WAIT_V(n) asm volatile("s_waitcnt vmcnt(" #n ")" ::: "memory")
; #define PG8_WAIT_L(n) asm volatile("s_waitcnt lgkmcnt(" #n ")" ::: "memory")
; template <class Epi, class Sched, bool ALIGN_EPI = false, bool SP2 = false>
; __device__ __forceinline__ void gemm_phase(PG8_LAS unsigned char* lds, const Gemm g, const Sched& S, const Epi& E, int tid_) {
;     ...
;             const bool last = (t == nt - 2);
;             const char* a1 = cA + (size_t)(t + 1) * kstep;
;             const char* a2 = last ? nA : cA + (size_t)(t + 2) * kstep; const char* b2 = last ? nB : cB + (size_t)(t + 2) * kstep;
;             const char* a3 = a2 + kstep; const char* b3 = b2 + kstep;
;             if (last && has_next) S.a_ready(nxt);
;             if constexpr (SP2) {
;             PG8_LDB(B0, 0, 0); PG8_LDB(B1, 0, 1); PG8_SCHED; PG8_LDA(At, 0, 0); PG8_STAGE(PG8_SA(1, 1), a1 + hstep, voffA);
;             PG8_WAIT_V(8); PG8_WAIT_L(0); PG8_BAR; PG8_MMA(0, 0, At, B0); PG8_MMA(0, 1, At, B1); PG8_BAR; PG8_SCHED;
;             PG8_LDA(At, 0, 1); PG8_STAGE(PG8_SB(0, 0), b2, voffB); PG8_STAGE(PG8_SB(0, 1), b2 + hstep, voffB); PG8_STAGE(PG8_SA(0, 0), a2, voffA);
;             PG8_WAIT_V(8); PG8_WAIT_L(0); PG8_BAR; PG8_MMA(1, 0, At, B0); PG8_MMA(1, 1, At, B1); PG8_BAR; PG8_SCHED;
.LBB0_526:
	v_add_u32_e32 v156, 0x10000, v145
	v_add_u32_e32 v172, 0x14000, v145
	ds_read_b128 v[140:143], v156
	ds_read_b128 v[148:151], v156 offset:1024
	ds_read_b128 v[152:155], v156 offset:2048
	ds_read_b128 v[156:159], v156 offset:3072
	ds_read_b128 v[160:163], v172
	ds_read_b128 v[164:167], v172 offset:1024
	ds_read_b128 v[168:171], v172 offset:2048
	ds_read_b128 v[172:175], v172 offset:3072
	s_add_u32 s21, s54, 0xfffc0080
	s_addc_u32 s56, s55, -1
	s_add_i32 s75, 0, 0x10000
	s_cmp_eq_u32 s74, 12
	s_cselect_b32 s59, s47, s56
	s_cselect_b32 s58, s70, s21
	s_cselect_b32 s57, s45, s73
	s_cselect_b32 s56, s71, s72
	s_add_i32 s21, 0, 0x14000
	v_lshl_add_u64 v[232:233], s[54:55], 0, v[138:139]
	s_add_i32 m0, s13, 0xc000
	ds_read_b128 v[176:179], v147
	ds_read_b128 v[180:183], v147 offset:1024
	ds_read_b128 v[184:187], v147 offset:2048
	ds_read_b128 v[188:191], v147 offset:3072
	ds_read_b128 v[200:203], v147 offset:4096
	ds_read_b128 v[204:207], v147 offset:5120
	ds_read_b128 v[208:211], v147 offset:6144
	ds_read_b128 v[214:217], v147 offset:7168
	global_load_lds_dwordx4 v[232:233], off
	s_add_i32 m0, s13, 0xe000
	v_lshl_add_u64 v[232:233], s[54:55], 0, v[136:137]
	global_load_lds_dwordx4 v[232:233], off
	s_waitcnt vmcnt(8)
	s_waitcnt lgkmcnt(0)
	s_barrier
	s_setprio 1
	s_waitcnt lgkmcnt(0)
	v_mfma_f32_16x16x32_bf16 v[126:129], v[140:143], v[176:179], v[126:129]
	v_mfma_f32_16x16x32_bf16 v[118:121], v[152:155], v[176:179], v[118:121]
	v_mfma_f32_16x16x32_bf16 v[110:113], v[140:143], v[184:187], v[110:113]
	v_mfma_f32_16x16x32_bf16 v[102:105], v[152:155], v[184:187], v[102:105]
	v_mfma_f32_16x16x32_bf16 v[94:97], v[140:143], v[200:203], v[94:97]
	v_mfma_f32_16x16x32_bf16 v[86:89], v[152:155], v[200:203], v[86:89]
	v_mfma_f32_16x16x32_bf16 v[78:81], v[140:143], v[208:211], v[78:81]
	v_mfma_f32_16x16x32_bf16 v[70:73], v[152:155], v[208:211], v[70:73]
	v_mfma_f32_16x16x32_bf16 v[126:129], v[148:151], v[180:183], v[126:129]
	v_mfma_f32_16x16x32_bf16 v[118:121], v[156:159], v[180:183], v[118:121]
	v_mfma_f32_16x16x32_bf16 v[110:113], v[148:151], v[188:191], v[110:113]
	v_mfma_f32_16x16x32_bf16 v[102:105], v[156:159], v[188:191], v[102:105]
	v_mfma_f32_16x16x32_bf16 v[94:97], v[148:151], v[204:207], v[94:97]
	v_mfma_f32_16x16x32_bf16 v[86:89], v[156:159], v[204:207], v[86:89]
	v_mfma_f32_16x16x32_bf16 v[78:81], v[148:151], v[214:217], v[78:81]
	v_mfma_f32_16x16x32_bf16 v[70:73], v[156:159], v[214:217], v[70:73]
	s_setprio 0
	s_setprio 1
	v_mfma_f32_16x16x32_bf16 v[122:125], v[160:163], v[176:179], v[122:125]
	v_mfma_f32_16x16x32_bf16 v[114:117], v[168:171], v[176:179], v[114:117]
	v_mfma_f32_16x16x32_bf16 v[106:109], v[160:163], v[184:187], v[106:109]
	v_mfma_f32_16x16x32_bf16 v[98:101], v[168:171], v[184:187], v[98:101]
	v_mfma_f32_16x16x32_bf16 v[90:93], v[160:163], v[200:203], v[90:93]
	v_mfma_f32_16x16x32_bf16 v[82:85], v[168:171], v[200:203], v[82:85]
	v_mfma_f32_16x16x32_bf16 v[74:77], v[160:163], v[208:211], v[74:77]
	v_mfma_f32_16x16x32_bf16 v[66:69], v[168:171], v[208:211], v[66:69]
	v_mfma_f32_16x16x32_bf16 v[122:125], v[164:167], v[180:183], v[122:125]
	v_mfma_f32_16x16x32_bf16 v[114:117], v[172:175], v[180:183], v[114:117]
	v_mfma_f32_16x16x32_bf16 v[106:109], v[164:167], v[188:191], v[106:109]
	v_mfma_f32_16x16x32_bf16 v[98:101], v[172:175], v[188:191], v[98:101]
	v_mfma_f32_16x16x32_bf16 v[90:93], v[164:167], v[204:207], v[90:93]
	v_mfma_f32_16x16x32_bf16 v[82:85], v[172:175], v[204:207], v[82:85]
	v_mfma_f32_16x16x32_bf16 v[74:77], v[164:167], v[214:217], v[74:77]
	v_mfma_f32_16x16x32_bf16 v[66:69], v[172:175], v[214:217], v[66:69]
	s_setprio 0
	s_barrier
	s_add_i32 s75, s75, s9
	v_lshl_add_u64 v[232:233], s[56:57], 0, v[0:1]
	s_mov_b32 m0, s75
	ds_read_b128 v[176:179], v147 offset:16384
	ds_read_b128 v[180:183], v147 offset:17408
	ds_read_b128 v[184:187], v147 offset:18432
	ds_read_b128 v[188:191], v147 offset:19456
	ds_read_b128 v[200:203], v147 offset:20480
	ds_read_b128 v[204:207], v147 offset:21504
	ds_read_b128 v[208:211], v147 offset:22528
	ds_read_b128 v[214:217], v147 offset:23552
	global_load_lds_dwordx4 v[232:233], off
	s_add_i32 m0, s75, 0x2000
	s_add_u32 s80, s56, 0x40000
	v_lshl_add_u64 v[234:235], s[56:57], 0, v[130:131]
	s_addc_u32 s81, s57, 0
	s_add_i32 s21, s21, s9
	global_load_lds_dwordx4 v[234:235], off
	v_lshl_add_u64 v[236:237], s[80:81], 0, v[0:1]
	s_mov_b32 m0, s21
	v_lshl_add_u64 v[238:239], s[58:59], 0, v[132:133]
	global_load_lds_dwordx4 v[236:237], off
	s_add_i32 m0, s21, 0x2000
	v_lshl_add_u64 v[236:237], s[80:81], 0, v[130:131]
	global_load_lds_dwordx4 v[236:237], off
	v_lshl_add_u64 v[236:237], s[58:59], 0, v[134:135]
	s_mov_b32 m0, s13
	s_nop 0
	global_load_lds_dwordx4 v[236:237], off
	s_mov_b32 m0, s14
	s_nop 0
	global_load_lds_dwordx4 v[238:239], off
	s_waitcnt vmcnt(8)
	s_waitcnt lgkmcnt(0)
	s_barrier
; #define PG8_STAGE(bufoff, gbase, voff) do { _Pragma("unroll") for (int _i = 0; _i < 2; ++_i) \
;         __builtin_amdgcn_global_load_lds((const unsigned*)((const char*)(gbase) + (voff)[_i]), (PG8_LAS unsigned*)(lds + (bufoff) + ldsw + _i * 8192), 16, 0, 0); } while (0)
; #define PG8_LDA(dst, b, h) do { _Pragma("unroll") for (int m = 0; m < 4; ++m) _Pragma("unroll") for (int k = 0; k < 2; ++k) dst[m][k] = *(const PG8_LAS bf16x8*)(lds + PG8_SA(b, h) + aoff + m * 2048 + k * 1024); } while (0)
; #define PG8_LDB(dst, b, h) do { _Pragma("unroll") for (int n = 0; n < 2; ++n) _Pragma("unroll") for (int k = 0; k < 2; ++k) dst[n][k] = *(const PG8_LAS bf16x8*)(lds + PG8_SB(b, h) + boff + n * 2048 + k * 1024); } while (0)
; #define PG8_MMA(ai, bj, At, Bt) do { __builtin_amdgcn_s_setprio(1); _Pragma("unroll") for (int m = 0; m < 4; ++m) _Pragma("unroll") for (int n = 0; n < 2; ++n) _Pragma("unroll") for (int k = 0; k < 2; ++k) \
;         acc[ai][bj][m][n] = __builtin_amdgcn_mfma_f32_16x16x32_bf16(Bt[n][k], At[m][k], acc[ai][bj][m][n], 0, 0, 0); __builtin_amdgcn_s_setprio(0); } while (0)
; #define PG8_WAIT_V(n) asm volatile("s_waitcnt vmcnt(" #n ")" ::: "memory")
; #define PG8_WAIT_L(n) asm volatile("s_waitcnt lgkmcnt(" #n ")" ::: "memory")
; #define PG8_BAR __builtin_amdgcn_s_barrier()
; #define PG8_SCHED __builtin_amdgcn_sched_barrier(0)
; template <class Epi, class Sched, bool ALIGN_EPI = false, bool SP2 = false>
; __device__ __forceinline__ void gemm_phase(PG8_LAS unsigned char* lds, const Gemm g, const Sched& S, const Epi& E, int tid_) {
;     ...
;             PG8_WAIT_V(8); PG8_WAIT_L(0); PG8_BAR; PG8_MMA(1, 0, At, B0); PG8_MMA(1, 1, At, B1); PG8_BAR; PG8_SCHED;
;             PG8_LDB(B0, 1, 0); PG8_LDB(B1, 1, 1); PG8_SCHED; PG8_LDA(At, 1, 0); PG8_STAGE(PG8_SA(0, 1), a2 + hstep, voffA);
;             PG8_WAIT_V(8); PG8_WAIT_L(0); PG8_BAR; PG8_MMA(0, 0, At, B0); PG8_MMA(0, 1, At, B1); PG8_BAR; PG8_SCHED;
	s_setprio 1
	s_waitcnt lgkmcnt(0)
	v_mfma_f32_16x16x32_bf16 v[62:65], v[140:143], v[176:179], v[62:65]
	v_mfma_f32_16x16x32_bf16 v[54:57], v[152:155], v[176:179], v[54:57]
	v_mfma_f32_16x16x32_bf16 v[46:49], v[140:143], v[184:187], v[46:49]
	v_mfma_f32_16x16x32_bf16 v[38:41], v[152:155], v[184:187], v[38:41]
	v_mfma_f32_16x16x32_bf16 v[30:33], v[140:143], v[200:203], v[30:33]
	v_mfma_f32_16x16x32_bf16 v[22:25], v[152:155], v[200:203], v[22:25]
	v_mfma_f32_16x16x32_bf16 v[14:17], v[140:143], v[208:211], v[14:17]
	v_mfma_f32_16x16x32_bf16 v[6:9], v[152:155], v[208:211], v[6:9]
	v_mfma_f32_16x16x32_bf16 v[62:65], v[148:151], v[180:183], v[62:65]
	v_mfma_f32_16x16x32_bf16 v[54:57], v[156:159], v[180:183], v[54:57]
	v_mfma_f32_16x16x32_bf16 v[46:49], v[148:151], v[188:191], v[46:49]
	v_mfma_f32_16x16x32_bf16 v[38:41], v[156:159], v[188:191], v[38:41]
	v_mfma_f32_16x16x32_bf16 v[30:33], v[148:151], v[204:207], v[30:33]
	v_mfma_f32_16x16x32_bf16 v[22:25], v[156:159], v[204:207], v[22:25]
	v_mfma_f32_16x16x32_bf16 v[14:17], v[148:151], v[214:217], v[14:17]
	v_mfma_f32_16x16x32_bf16 v[6:9], v[156:159], v[214:217], v[6:9]
	s_setprio 0
	s_setprio 1
	v_mfma_f32_16x16x32_bf16 v[58:61], v[160:163], v[176:179], v[58:61]
	v_mfma_f32_16x16x32_bf16 v[50:53], v[168:171], v[176:179], v[50:53]
	v_mfma_f32_16x16x32_bf16 v[42:45], v[160:163], v[184:187], v[42:45]
	v_mfma_f32_16x16x32_bf16 v[34:37], v[168:171], v[184:187], v[34:37]
	v_mfma_f32_16x16x32_bf16 v[26:29], v[160:163], v[200:203], v[26:29]
	v_mfma_f32_16x16x32_bf16 v[18:21], v[168:171], v[200:203], v[18:21]
	v_mfma_f32_16x16x32_bf16 v[10:13], v[160:163], v[208:211], v[10:13]
	v_mfma_f32_16x16x32_bf16 v[2:5], v[168:171], v[208:211], v[2:5]
	v_mfma_f32_16x16x32_bf16 v[58:61], v[164:167], v[180:183], v[58:61]
	v_mfma_f32_16x16x32_bf16 v[50:53], v[172:175], v[180:183], v[50:53]
	v_mfma_f32_16x16x32_bf16 v[42:45], v[164:167], v[188:191], v[42:45]
	v_mfma_f32_16x16x32_bf16 v[34:37], v[172:175], v[188:191], v[34:37]
	v_mfma_f32_16x16x32_bf16 v[26:29], v[164:167], v[204:207], v[26:29]
	v_mfma_f32_16x16x32_bf16 v[18:21], v[172:175], v[204:207], v[18:21]
	v_mfma_f32_16x16x32_bf16 v[10:13], v[164:167], v[214:217], v[10:13]
	v_mfma_f32_16x16x32_bf16 v[2:5], v[172:175], v[214:217], v[2:5]
	s_setprio 0
	s_barrier
	s_add_i32 s21, 0, 0x18000
	s_add_i32 s75, 0, 0x1c000
	v_add_u32_e32 v156, s21, v145
	v_add_u32_e32 v172, s75, v145
	ds_read_b128 v[140:143], v156
	ds_read_b128 v[148:151], v156 offset:1024
	ds_read_b128 v[152:155], v156 offset:2048
	ds_read_b128 v[156:159], v156 offset:3072
	ds_read_b128 v[160:163], v172
	ds_read_b128 v[164:167], v172 offset:1024
	ds_read_b128 v[168:171], v172 offset:2048
	ds_read_b128 v[172:175], v172 offset:3072
	s_add_u32 s58, s58, 0x40000
	s_addc_u32 s59, s59, 0
	s_mov_b32 m0, s15
	v_lshl_add_u64 v[240:241], s[58:59], 0, v[134:135]
	ds_read_b128 v[176:179], v147 offset:32768
	ds_read_b128 v[180:183], v147 offset:33792
	ds_read_b128 v[184:187], v147 offset:34816
	ds_read_b128 v[188:191], v147 offset:35840
	ds_read_b128 v[200:203], v147 offset:36864
	ds_read_b128 v[204:207], v147 offset:37888
	ds_read_b128 v[208:211], v147 offset:38912
	ds_read_b128 v[214:217], v147 offset:39936
	global_load_lds_dwordx4 v[240:241], off
	v_lshl_add_u64 v[240:241], s[58:59], 0, v[132:133]
	s_mov_b32 m0, s60
	s_nop 0
	global_load_lds_dwordx4 v[240:241], off
	s_waitcnt vmcnt(8)
	s_waitcnt lgkmcnt(0)
	s_barrier
	s_setprio 1
	s_waitcnt lgkmcnt(0)
	v_mfma_f32_16x16x32_bf16 v[126:129], v[140:143], v[176:179], v[126:129]
	v_mfma_f32_16x16x32_bf16 v[118:121], v[152:155], v[176:179], v[118:121]
	v_mfma_f32_16x16x32_bf16 v[110:113], v[140:143], v[184:187], v[110:113]
	v_mfma_f32_16x16x32_bf16 v[102:105], v[152:155], v[184:187], v[102:105]
	v_mfma_f32_16x16x32_bf16 v[94:97], v[140:143], v[200:203], v[94:97]
	v_mfma_f32_16x16x32_bf16 v[86:89], v[152:155], v[200:203], v[86:89]
	v_mfma_f32_16x16x32_bf16 v[78:81], v[140:143], v[208:211], v[78:81]
	v_mfma_f32_16x16x32_bf16 v[70:73], v[152:155], v[208:211], v[70:73]
	v_mfma_f32_16x16x32_bf16 v[126:129], v[148:151], v[180:183], v[126:129]
	v_mfma_f32_16x16x32_bf16 v[118:121], v[156:159], v[180:183], v[118:121]
	v_mfma_f32_16x16x32_bf16 v[110:113], v[148:151], v[188:191], v[110:113]
	v_mfma_f32_16x16x32_bf16 v[102:105], v[156:159], v[188:191], v[102:105]
	v_mfma_f32_16x16x32_bf16 v[94:97], v[148:151], v[204:207], v[94:97]
	v_mfma_f32_16x16x32_bf16 v[86:89], v[156:159], v[204:207], v[86:89]
	v_mfma_f32_16x16x32_bf16 v[78:81], v[148:151], v[214:217], v[78:81]
	v_mfma_f32_16x16x32_bf16 v[70:73], v[156:159], v[214:217], v[70:73]
	s_setprio 0
	s_setprio 1
	v_mfma_f32_16x16x32_bf16 v[122:125], v[160:163], v[176:179], v[122:125]
	v_mfma_f32_16x16x32_bf16 v[114:117], v[168:171], v[176:179], v[114:117]
	v_mfma_f32_16x16x32_bf16 v[106:109], v[160:163], v[184:187], v[106:109]
	v_mfma_f32_16x16x32_bf16 v[98:101], v[168:171], v[184:187], v[98:101]
	v_mfma_f32_16x16x32_bf16 v[90:93], v[160:163], v[200:203], v[90:93]
	v_mfma_f32_16x16x32_bf16 v[82:85], v[168:171], v[200:203], v[82:85]
	v_mfma_f32_16x16x32_bf16 v[74:77], v[160:163], v[208:211], v[74:77]
	v_mfma_f32_16x16x32_bf16 v[66:69], v[168:171], v[208:211], v[66:69]
	v_mfma_f32_16x16x32_bf16 v[122:125], v[164:167], v[180:183], v[122:125]
	v_mfma_f32_16x16x32_bf16 v[114:117], v[172:175], v[180:183], v[114:117]
	v_mfma_f32_16x16x32_bf16 v[106:109], v[164:167], v[188:191], v[106:109]
	v_mfma_f32_16x16x32_bf16 v[98:101], v[172:175], v[188:191], v[98:101]
	v_mfma_f32_16x16x32_bf16 v[90:93], v[164:167], v[204:207], v[90:93]
	v_mfma_f32_16x16x32_bf16 v[82:85], v[172:175], v[204:207], v[82:85]
	v_mfma_f32_16x16x32_bf16 v[74:77], v[164:167], v[214:217], v[74:77]
	v_mfma_f32_16x16x32_bf16 v[66:69], v[172:175], v[214:217], v[66:69]
	s_setprio 0
	s_barrier
; #define PG8_STAGE(bufoff, gbase, voff) do { _Pragma("unroll") for (int _i = 0; _i < 2; ++_i) \
;         __builtin_amdgcn_global_load_lds((const unsigned*)((const char*)(gbase) + (voff)[_i]), (PG8_LAS unsigned*)(lds + (bufoff) + ldsw + _i * 8192), 16, 0, 0); } while (0)
; #define PG8_LDA(dst, b, h) do { _Pragma("unroll") for (int m = 0; m < 4; ++m) _Pragma("unroll") for (int k = 0; k < 2; ++k) dst[m][k] = *(const PG8_LAS bf16x8*)(lds + PG8_SA(b, h) + aoff + m * 2048 + k * 1024); } while (0)
; #define PG8_MMA(ai, bj, At, Bt) do { __builtin_amdgcn_s_setprio(1); _Pragma("unroll") for (int m = 0; m < 4; ++m) _Pragma("unroll") for (int n = 0; n < 2; ++n) _Pragma("unroll") for (int k = 0; k < 2; ++k) \
;         acc[ai][bj][m][n] = __builtin_amdgcn_mfma_f32_16x16x32_bf16(Bt[n][k], At[m][k], acc[ai][bj][m][n], 0, 0, 0); __builtin_amdgcn_s_setprio(0); } while (0)
; #define PG8_WAIT_V(n) asm volatile("s_waitcnt vmcnt(" #n ")" ::: "memory")
; #define PG8_WAIT_L(n) asm volatile("s_waitcnt lgkmcnt(" #n ")" ::: "memory")
; #define PG8_BAR __builtin_amdgcn_s_barrier()
; #define PG8_SCHED __builtin_amdgcn_sched_barrier(0)
; template <class Epi, class Sched, bool ALIGN_EPI = false, bool SP2 = false>
; __device__ __forceinline__ void gemm_phase(PG8_LAS unsigned char* lds, const Gemm g, const Sched& S, const Epi& E, int tid_) {
;     ...
;             PG8_LDA(At, 1, 1); PG8_STAGE(PG8_SB(1, 0), b3, voffB); PG8_STAGE(PG8_SB(1, 1), b3 + hstep, voffB); PG8_STAGE(PG8_SA(1, 0), a3, voffA);
;             PG8_WAIT_V(8); PG8_WAIT_L(0); PG8_BAR; PG8_MMA(1, 0, At, B0); PG8_MMA(1, 1, At, B1); PG8_BAR; PG8_SCHED;
;     ...
;         if constexpr (ALIGN_EPI) { if (wr == 0) PG8_BAR; }
	s_add_i32 s21, s21, s9
	v_lshl_add_u64 v[232:233], v[232:233], 0, s[28:29]
	s_mov_b32 m0, s21
	ds_read_b128 v[176:179], v147 offset:49152
	ds_read_b128 v[180:183], v147 offset:50176
	ds_read_b128 v[184:187], v147 offset:51200
	ds_read_b128 v[188:191], v147 offset:52224
	ds_read_b128 v[200:203], v147 offset:53248
	ds_read_b128 v[204:207], v147 offset:54272
	ds_read_b128 v[208:211], v147 offset:55296
	ds_read_b128 v[214:217], v147 offset:56320
	global_load_lds_dwordx4 v[232:233], off
	s_add_i32 m0, s21, 0x2000
	s_add_u32 s56, s56, 0x40080
	v_lshl_add_u64 v[232:233], v[234:235], 0, s[28:29]
	s_addc_u32 s57, s57, 0
	s_add_i32 s21, s75, s9
	global_load_lds_dwordx4 v[232:233], off
	v_lshl_add_u64 v[232:233], s[56:57], 0, v[0:1]
	s_mov_b32 m0, s21
	s_nop 0
	global_load_lds_dwordx4 v[232:233], off
	s_add_i32 m0, s21, 0x2000
	v_lshl_add_u64 v[232:233], s[56:57], 0, v[130:131]
	global_load_lds_dwordx4 v[232:233], off
	v_lshl_add_u64 v[232:233], v[236:237], 0, s[28:29]
	s_mov_b32 m0, s61
	s_nop 0
	global_load_lds_dwordx4 v[232:233], off
	v_lshl_add_u64 v[232:233], v[238:239], 0, s[28:29]
	s_mov_b32 m0, s64
	s_nop 0
	global_load_lds_dwordx4 v[232:233], off
	s_waitcnt vmcnt(8)
	s_waitcnt lgkmcnt(0)
	s_barrier
	s_setprio 1
	s_waitcnt lgkmcnt(0)
	v_mfma_f32_16x16x32_bf16 v[62:65], v[140:143], v[176:179], v[62:65]
	v_mfma_f32_16x16x32_bf16 v[54:57], v[152:155], v[176:179], v[54:57]
	v_mfma_f32_16x16x32_bf16 v[46:49], v[140:143], v[184:187], v[46:49]
	v_mfma_f32_16x16x32_bf16 v[38:41], v[152:155], v[184:187], v[38:41]
	v_mfma_f32_16x16x32_bf16 v[30:33], v[140:143], v[200:203], v[30:33]
	v_mfma_f32_16x16x32_bf16 v[22:25], v[152:155], v[200:203], v[22:25]
	v_mfma_f32_16x16x32_bf16 v[14:17], v[140:143], v[208:211], v[14:17]
	v_mfma_f32_16x16x32_bf16 v[6:9], v[152:155], v[208:211], v[6:9]
	v_mfma_f32_16x16x32_bf16 v[62:65], v[148:151], v[180:183], v[62:65]
	v_mfma_f32_16x16x32_bf16 v[54:57], v[156:159], v[180:183], v[54:57]
	v_mfma_f32_16x16x32_bf16 v[46:49], v[148:151], v[188:191], v[46:49]
	v_mfma_f32_16x16x32_bf16 v[38:41], v[156:159], v[188:191], v[38:41]
	v_mfma_f32_16x16x32_bf16 v[30:33], v[148:151], v[204:207], v[30:33]
	v_mfma_f32_16x16x32_bf16 v[22:25], v[156:159], v[204:207], v[22:25]
	v_mfma_f32_16x16x32_bf16 v[14:17], v[148:151], v[214:217], v[14:17]
	v_mfma_f32_16x16x32_bf16 v[6:9], v[156:159], v[214:217], v[6:9]
	s_setprio 0
	s_setprio 1
	v_mfma_f32_16x16x32_bf16 v[58:61], v[160:163], v[176:179], v[58:61]
	v_mfma_f32_16x16x32_bf16 v[50:53], v[168:171], v[176:179], v[50:53]
	v_mfma_f32_16x16x32_bf16 v[42:45], v[160:163], v[184:187], v[42:45]
	v_mfma_f32_16x16x32_bf16 v[34:37], v[168:171], v[184:187], v[34:37]
	v_mfma_f32_16x16x32_bf16 v[26:29], v[160:163], v[200:203], v[26:29]
	v_mfma_f32_16x16x32_bf16 v[18:21], v[168:171], v[200:203], v[18:21]
	v_mfma_f32_16x16x32_bf16 v[10:13], v[160:163], v[208:211], v[10:13]
	v_mfma_f32_16x16x32_bf16 v[2:5], v[168:171], v[208:211], v[2:5]
	v_mfma_f32_16x16x32_bf16 v[58:61], v[164:167], v[180:183], v[58:61]
	v_mfma_f32_16x16x32_bf16 v[50:53], v[172:175], v[180:183], v[50:53]
	v_mfma_f32_16x16x32_bf16 v[42:45], v[164:167], v[188:191], v[42:45]
	v_mfma_f32_16x16x32_bf16 v[34:37], v[172:175], v[188:191], v[34:37]
	v_mfma_f32_16x16x32_bf16 v[26:29], v[164:167], v[204:207], v[26:29]
	v_mfma_f32_16x16x32_bf16 v[18:21], v[172:175], v[204:207], v[18:21]
	v_mfma_f32_16x16x32_bf16 v[10:13], v[164:167], v[214:217], v[10:13]
	v_mfma_f32_16x16x32_bf16 v[2:5], v[172:175], v[214:217], v[2:5]
	s_setprio 0
	s_barrier
	s_add_i32 s74, s74, 2
	s_add_u32 s72, s72, 0x100
	s_addc_u32 s73, s73, 0
	s_add_u32 s54, s54, 0x100
	s_addc_u32 s55, s55, 0
	s_cmp_gt_u32 s74, 13
	s_cbranch_scc0 .LBB0_526
	s_and_b64 vcc, exec, s[42:43]
	s_cbranch_vccz .LBB0_529
	s_barrier
